# attention: V^T LDS tile re-pitched 144->160 B (bank-conflict-free ds_read_b128 in P*V), P*V reads issued ahead of MFMAs
# speedup vs baseline: 1.0037x; 1.0037x over previous
; #define LAS __attribute__((address_space(3)))
; __device__ __forceinline__ f32x4 mfma16(bf16x8 a, bf16x8 b, f32x4 c) { return __builtin_amdgcn_mfma_f32_16x16x32_bf16(a, b, c, 0, 0, 0); }
; template <bool CTXQ>
; __device__ __forceinline__ void attn_super(const bf16_t* QO, bf16_t* OO, const bf16_t* Kb, const bf16_t* VT, const float* rpb, LAS unsigned char* lds, int tid_, int lane_, int wave, int st) {
;     ...
;     for (int i = I0; i < 13; ++i) { const int c = tid + 512 * i, t = c >> 3, cc = c & 7; *(LAS u32x4*)(lds + t * AT_PITCH + cc * 16) = stg[i]; }
;     __syncthreads();
;     const int qcol = q0 + q, wstart = min(max(qcol - 8, 0), 48);
;     const int koff = 8 * (q >> 2) + (q & 3);
;     const LAS float* bptr[2][4]; float madd[2][4];
; #pragma unroll
;     for (int T = 0; T < 2; ++T)
; #pragma unroll
;         for (int j = 0; j < 4; ++j) { const int kcol = ks + 8 * g + 4 * T + j; const bool ok = (kcol >= wstart) && (kcol < wstart + 16);
;             const int dcol = min(max(kcol - qcol + 15, 0), 30);
;             bptr[T][j] = rpl + (rs - r + 7) * 31 + dcol; madd[T][j] = ok ? 0.0f : -1e30f; }
;     f32x4 S[16][2];
; #pragma unroll
;     for (int grp = G0; grp < 16; ++grp) {
;         const int tb = grp < 8 ? (krl0 + grp) * 64 + ks : 576 + 32 * (grp - 8);
; #pragma unroll
;         for (int T = 0; T < 2; ++T) {
;             const LAS unsigned char* kp = lds + (tb + koff + 4 * T) * AT_PITCH + g * 16;
;             const bf16x8 kf0 = *(const LAS bf16x8*)kp, kf1 = *(const LAS bf16x8*)(kp + 64);
;             f32x4 s = {0.f, 0.f, 0.f, 0.f};
;             s = mfma16(kf0, qf0, s); s = mfma16(kf1, qf1, s);
;             if (grp < 8) {
; #pragma unroll
;                 for (int j = 0; j < 4; ++j) s[j] += bptr[T][j][grp * 31] + madd[T][j];
;             }
;             S[grp][T] = s;
.LBB0_166:
	s_or_b64 exec, exec, s[2:3]
	v_lshlrev_b32_e32 v65, 4, v104
	v_and_b32_e32 v65, 0x70, v65
	v_add_u32_e32 v102, 0, v65
	v_lshlrev_b64 v[100:101], 10, v[88:89]
	v_mad_u64_u32 v[88:89], s[2:3], v62, s5, v[102:103]
	s_waitcnt vmcnt(14)
	ds_write_b128 v88, v[8:11]
	v_mad_u64_u32 v[8:9], s[2:3], v64, s5, v[102:103]
	s_waitcnt vmcnt(13)
	ds_write_b128 v8, v[12:15]
	v_mad_u64_u32 v[8:9], s[2:3], v66, s5, v[102:103]
	s_waitcnt vmcnt(12)
	ds_write_b128 v8, v[16:19]
	v_mad_u64_u32 v[8:9], s[2:3], v68, s5, v[102:103]
	s_waitcnt vmcnt(11)
	ds_write_b128 v8, v[20:23]
	v_mad_u64_u32 v[8:9], s[2:3], v70, s5, v[102:103]
	s_waitcnt vmcnt(10)
	ds_write_b128 v8, v[24:27]
	v_mad_u64_u32 v[8:9], s[2:3], v72, s5, v[102:103]
	s_waitcnt vmcnt(9)
	ds_write_b128 v8, v[28:31]
	v_mad_u64_u32 v[8:9], s[2:3], v74, s5, v[102:103]
	s_waitcnt vmcnt(8)
	ds_write_b128 v8, v[32:35]
	v_mad_u64_u32 v[8:9], s[2:3], v76, s5, v[102:103]
	s_waitcnt vmcnt(7)
	ds_write_b128 v8, v[36:39]
	v_mad_u64_u32 v[8:9], s[2:3], v78, s5, v[102:103]
	s_waitcnt vmcnt(6)
	ds_write_b128 v8, v[40:43]
	v_mad_u64_u32 v[8:9], s[2:3], v80, s5, v[102:103]
	v_lshlrev_b32_e32 v98, 3, v63
	s_waitcnt vmcnt(5)
	ds_write_b128 v8, v[44:47]
	v_mad_u64_u32 v[8:9], s[2:3], v82, s5, v[102:103]
	s_waitcnt vmcnt(4)
	ds_write_b128 v8, v[50:53]
	v_mad_u64_u32 v[8:9], s[2:3], v84, s5, v[102:103]
	v_or_b32_e32 v16, s18, v99
	v_add_u32_e32 v105, s25, v98
	s_waitcnt vmcnt(3)
	ds_write_b128 v8, v[54:57]
	v_mad_u64_u32 v[8:9], s[2:3], v86, s5, v[102:103]
	v_sub_u32_e32 v10, v105, v16
	s_waitcnt vmcnt(2)
	ds_write_b128 v8, v[58:61]
	v_sub_u32_e64 v8, v16, 8 clamp
	v_max_i32_e32 v10, -15, v10
	v_min_u32_e32 v12, 48, v8
	v_add_u32_e32 v10, 15, v10
	v_add_u32_e32 v13, 16, v12
	v_min_u32_e32 v10, 30, v10
	v_cmp_ge_u32_e32 vcc, v105, v12
	v_cmp_lt_u32_e64 s[40:41], v105, v13
	v_lshl_add_u32 v41, v10, 2, s28
	v_or_b32_e32 v10, 1, v105
	s_and_b64 s[2:3], vcc, s[40:41]
	v_cmp_ge_u32_e32 vcc, v10, v12
	v_cmp_lt_u32_e64 s[40:41], v10, v13
	v_sub_u32_e32 v10, v10, v16
	v_max_i32_e32 v10, -15, v10
	v_add_u32_e32 v10, 15, v10
	v_min_u32_e32 v10, 30, v10
	v_lshl_add_u32 v43, v10, 2, s28
	v_or_b32_e32 v10, 2, v105
	v_cndmask_b32_e64 v42, v233, 0, s[2:3]
	s_and_b64 s[2:3], vcc, s[40:41]
	v_cmp_ge_u32_e32 vcc, v10, v12
	v_cmp_lt_u32_e64 s[40:41], v10, v13
	v_sub_u32_e32 v10, v10, v16
	v_max_i32_e32 v10, -15, v10
	v_add_u32_e32 v10, 15, v10
	v_min_u32_e32 v10, 30, v10
	v_lshl_add_u32 v45, v10, 2, s28
	v_or_b32_e32 v10, 3, v105
	v_cndmask_b32_e64 v44, v233, 0, s[2:3]
	s_and_b64 s[2:3], vcc, s[40:41]
	v_cmp_ge_u32_e32 vcc, v10, v12
	v_cmp_lt_u32_e64 s[40:41], v10, v13
	v_sub_u32_e32 v10, v10, v16
	v_max_i32_e32 v10, -15, v10
	v_add_u32_e32 v10, 15, v10
	v_min_u32_e32 v10, 30, v10
	v_lshl_add_u32 v47, v10, 2, s28
	v_or_b32_e32 v10, 4, v105
	v_cndmask_b32_e64 v46, v233, 0, s[2:3]
	s_and_b64 s[2:3], vcc, s[40:41]
	v_cmp_ge_u32_e32 vcc, v10, v12
	v_cmp_lt_u32_e64 s[40:41], v10, v13
	v_sub_u32_e32 v10, v10, v16
	v_max_i32_e32 v10, -15, v10
	v_add_u32_e32 v10, 15, v10
	v_min_u32_e32 v10, 30, v10
	v_lshl_add_u32 v38, v10, 2, s28
	v_or_b32_e32 v10, 5, v105
	v_cndmask_b32_e64 v50, v233, 0, s[2:3]
	s_and_b64 s[2:3], vcc, s[40:41]
	v_cmp_ge_u32_e32 vcc, v10, v12
	v_cmp_lt_u32_e64 s[40:41], v10, v13
	v_sub_u32_e32 v10, v10, v16
	v_max_i32_e32 v10, -15, v10
	v_add_u32_e32 v10, 15, v10
	v_min_u32_e32 v10, 30, v10
	v_lshl_add_u32 v35, v10, 2, s28
	v_or_b32_e32 v10, 6, v105
	v_lshlrev_b32_e32 v8, 1, v99
	v_and_b32_e32 v9, 3, v104
	v_cndmask_b32_e64 v39, v233, 0, s[2:3]
	s_and_b64 s[2:3], vcc, s[40:41]
	v_cmp_ge_u32_e32 vcc, v10, v12
	v_cmp_lt_u32_e64 s[40:41], v10, v13
	v_sub_u32_e32 v10, v10, v16
	v_max_i32_e32 v10, -15, v10
	v_and_or_b32 v32, v8, 24, v9
	v_add_u32_e32 v10, 15, v10
	v_lshl_add_u32 v103, v63, 4, 0
	v_add_u32_e32 v8, s30, v32
	v_min_u32_e32 v10, 30, v10
	v_mad_i32_i24 v17, v8, s5, v103
	s_waitcnt lgkmcnt(0)
	s_barrier
	v_lshl_add_u32 v34, v10, 2, s28
	ds_read_b128 v[8:11], v17
	v_or_b32_e32 v18, 7, v105
	v_cndmask_b32_e64 v37, v233, 0, s[2:3]
	s_and_b64 s[2:3], vcc, s[40:41]
	v_cmp_ge_u32_e32 vcc, v18, v12
	v_cmp_lt_u32_e64 s[40:41], v18, v13
	ds_read_b128 v[12:15], v17 offset:64
	v_sub_u32_e32 v16, v18, v16
	s_waitcnt vmcnt(1) lgkmcnt(1)
	v_mfma_f32_16x16x32_bf16 v[8:11], v[8:11], v[4:7], 0
	v_max_i32_e32 v16, -15, v16
	v_add_u32_e32 v16, 15, v16
	v_min_u32_e32 v16, 30, v16
	v_lshl_add_u32 v40, v16, 2, s28
	s_waitcnt vmcnt(0) lgkmcnt(0)
	v_mfma_f32_16x16x32_bf16 v[8:11], v[12:15], v[0:3], v[8:11]
	ds_read_b128 v[12:15], v17 offset:576
	ds_read_b32 v16, v41 offset:868
	ds_read_b32 v18, v43 offset:868
	ds_read_b32 v24, v45 offset:868
	ds_read_b32 v25, v47 offset:868
	ds_read_b32 v26, v38 offset:868
	ds_read_b32 v27, v35 offset:868
	ds_read_b32 v28, v34 offset:868
	ds_read_b32 v29, v40 offset:868
	ds_read_b128 v[20:23], v17 offset:640
	s_waitcnt lgkmcnt(8)
	v_add_f32_e32 v16, v42, v16
	v_mfma_f32_16x16x32_bf16 v[12:15], v[12:15], v[4:7], 0
	v_add_f32_e32 v19, v8, v16
	s_waitcnt lgkmcnt(7)
	v_add_f32_e32 v8, v44, v18
	v_add_f32_e32 v18, v9, v8
	s_waitcnt lgkmcnt(0)
	v_mfma_f32_16x16x32_bf16 v[20:23], v[20:23], v[0:3], v[12:15]
	v_add_f32_e32 v8, v46, v24
	v_add_f32_e32 v17, v10, v8
	v_add_f32_e32 v8, v50, v25
	v_add_f32_e32 v16, v11, v8
	v_add_f32_e32 v8, v39, v26
	v_cndmask_b32_e64 v36, v233, 0, s[2:3]
	s_and_b64 s[2:3], vcc, s[40:41]
	s_nop 0
	v_add_f32_e32 v15, v20, v8
	v_add_f32_e32 v8, v37, v27
	v_cndmask_b32_e64 v33, v233, 0, s[2:3]
	v_add_f32_e32 v13, v21, v8
	v_add_f32_e32 v8, v36, v28
	v_add_f32_e32 v11, v22, v8
	v_add_f32_e32 v8, v33, v29
	v_add_f32_e32 v10, v23, v8
	v_add_u32_e32 v8, s34, v32
	v_mad_i32_i24 v28, v8, s5, v103
	ds_read_b128 v[20:23], v28
	ds_read_b128 v[24:27], v28 offset:64
	ds_read_b32 v8, v41 offset:992
	ds_read_b32 v9, v43 offset:992
	ds_read_b32 v12, v45 offset:992
	ds_read_b32 v14, v47 offset:992
	s_waitcnt lgkmcnt(5)
; #define LAS __attribute__((address_space(3)))
; __device__ __forceinline__ f32x4 mfma16(bf16x8 a, bf16x8 b, f32x4 c) { return __builtin_amdgcn_mfma_f32_16x16x32_bf16(a, b, c, 0, 0, 0); }
; template <bool CTXQ>
; __device__ __forceinline__ void attn_super(const bf16_t* QO, bf16_t* OO, const bf16_t* Kb, const bf16_t* VT, const float* rpb, LAS unsigned char* lds, int tid_, int lane_, int wave, int st) {
;     ...
;     for (int grp = G0; grp < 16; ++grp) {
;         const int tb = grp < 8 ? (krl0 + grp) * 64 + ks : 576 + 32 * (grp - 8);
; #pragma unroll
;         for (int T = 0; T < 2; ++T) {
;             const LAS unsigned char* kp = lds + (tb + koff + 4 * T) * AT_PITCH + g * 16;
;             const bf16x8 kf0 = *(const LAS bf16x8*)kp, kf1 = *(const LAS bf16x8*)(kp + 64);
;             f32x4 s = {0.f, 0.f, 0.f, 0.f};
;             s = mfma16(kf0, qf0, s); s = mfma16(kf1, qf1, s);
;             if (grp < 8) {
; #pragma unroll
;                 for (int j = 0; j < 4; ++j) s[j] += bptr[T][j][grp * 31] + madd[T][j];
;             }
;             S[grp][T] = s;
;         }
;         __builtin_amdgcn_sched_barrier(0);
;     }
	v_mfma_f32_16x16x32_bf16 v[20:23], v[20:23], v[4:7], 0
	s_waitcnt lgkmcnt(3)
	v_add_f32_e32 v8, v42, v8
	s_waitcnt lgkmcnt(2)
	v_add_f32_e32 v9, v44, v9
	s_waitcnt lgkmcnt(1)
	v_add_f32_e32 v12, v46, v12
	v_mfma_f32_16x16x32_bf16 v[20:23], v[24:27], v[0:3], v[20:23]
	s_waitcnt lgkmcnt(0)
	v_add_f32_e32 v14, v50, v14
	s_nop 5
	v_add_f32_e32 v8, v20, v8
	v_add_f32_e32 v9, v21, v9
	v_add_f32_e32 v12, v22, v12
	v_add_f32_e32 v14, v23, v14
	ds_read_b128 v[20:23], v28 offset:576
	ds_read_b128 v[24:27], v28 offset:640
	s_waitcnt lgkmcnt(1)
	v_mfma_f32_16x16x32_bf16 v[20:23], v[20:23], v[4:7], 0
	s_waitcnt lgkmcnt(0)
	v_mfma_f32_16x16x32_bf16 v[20:23], v[24:27], v[0:3], v[20:23]
	ds_read_b32 v24, v38 offset:992
	s_waitcnt lgkmcnt(0)
	v_add_f32_e32 v24, v39, v24
	s_nop 4
	v_add_f32_e32 v20, v20, v24
	ds_read_b32 v24, v35 offset:992
	s_waitcnt lgkmcnt(0)
	v_add_f32_e32 v24, v37, v24
	v_add_f32_e32 v21, v21, v24
	ds_read_b32 v24, v34 offset:992
	s_waitcnt lgkmcnt(0)
	v_add_f32_e32 v24, v36, v24
	v_add_f32_e32 v22, v22, v24
	ds_read_b32 v24, v40 offset:992
	s_waitcnt lgkmcnt(0)
	v_add_f32_e32 v24, v33, v24
	v_add_f32_e32 v25, v23, v24
	v_add_u32_e32 v23, s36, v32
	v_mad_i32_i24 v51, v23, s5, v103
	ds_read_b128 v[26:29], v51
	ds_read_b128 v[52:55], v51 offset:64
	ds_read_b32 v23, v41 offset:1116
	ds_read_b32 v24, v43 offset:1116
	s_waitcnt lgkmcnt(3)
	v_mfma_f32_16x16x32_bf16 v[26:29], v[26:29], v[4:7], 0
	s_waitcnt lgkmcnt(1)
	v_add_f32_e32 v23, v42, v23
	s_waitcnt lgkmcnt(0)
	v_add_f32_e32 v24, v44, v24
	v_mfma_f32_16x16x32_bf16 v[26:29], v[52:55], v[0:3], v[26:29]
	s_nop 7
	v_add_f32_e32 v23, v26, v23
	v_add_f32_e32 v24, v27, v24
	ds_read_b32 v26, v45 offset:1116
	ds_read_b32 v27, v47 offset:1116
	s_waitcnt lgkmcnt(1)
	v_add_f32_e32 v26, v46, v26
	s_waitcnt lgkmcnt(0)
	v_add_f32_e32 v27, v50, v27
	v_add_f32_e32 v26, v28, v26
	v_add_f32_e32 v27, v29, v27
	ds_read_b128 v[28:31], v51 offset:576
	ds_read_b128 v[52:55], v51 offset:640
	s_waitcnt lgkmcnt(1)
	v_mfma_f32_16x16x32_bf16 v[28:31], v[28:31], v[4:7], 0
	ds_read_b32 v51, v38 offset:1116
	s_waitcnt lgkmcnt(0)
	v_add_f32_e32 v51, v39, v51
	v_mfma_f32_16x16x32_bf16 v[28:31], v[52:55], v[0:3], v[28:31]
	s_nop 7
	v_add_f32_e32 v28, v28, v51
	ds_read_b32 v51, v35 offset:1116
	s_waitcnt lgkmcnt(0)
	v_add_f32_e32 v51, v37, v51
	v_add_f32_e32 v29, v29, v51
	ds_read_b32 v51, v34 offset:1116
	s_waitcnt lgkmcnt(0)
	v_add_f32_e32 v51, v36, v51
	v_add_f32_e32 v30, v30, v51
	ds_read_b32 v51, v40 offset:1116
	s_waitcnt lgkmcnt(0)
	v_add_f32_e32 v51, v33, v51
	v_add_f32_e32 v109, v31, v51
	v_add_u32_e32 v31, s38, v32
	v_mad_i32_i24 v51, v31, s5, v103
	ds_read_b128 v[52:55], v51
	ds_read_b128 v[56:59], v51 offset:64
	ds_read_b32 v31, v41 offset:1240
	s_waitcnt lgkmcnt(2)
	v_mfma_f32_16x16x32_bf16 v[52:55], v[52:55], v[4:7], 0
	s_waitcnt lgkmcnt(0)
	v_add_f32_e32 v31, v42, v31
	v_mfma_f32_16x16x32_bf16 v[52:55], v[56:59], v[0:3], v[52:55]
	s_nop 7
	v_add_f32_e32 v31, v52, v31
	ds_read_b32 v52, v43 offset:1240
	s_waitcnt lgkmcnt(0)
	v_add_f32_e32 v52, v44, v52
	v_add_f32_e32 v108, v53, v52
	ds_read_b32 v52, v45 offset:1240
	s_waitcnt lgkmcnt(0)
	v_add_f32_e32 v52, v46, v52
	v_add_f32_e32 v110, v54, v52
	ds_read_b32 v52, v47 offset:1240
	s_waitcnt lgkmcnt(0)
	v_add_f32_e32 v52, v50, v52
	v_add_f32_e32 v111, v55, v52
	ds_read_b128 v[52:55], v51 offset:576
	ds_read_b128 v[56:59], v51 offset:640
	s_waitcnt lgkmcnt(1)
	v_mfma_f32_16x16x32_bf16 v[52:55], v[52:55], v[4:7], 0
	ds_read_b32 v51, v38 offset:1240
	s_waitcnt lgkmcnt(0)
	v_add_f32_e32 v51, v39, v51
	v_mfma_f32_16x16x32_bf16 v[52:55], v[56:59], v[0:3], v[52:55]
	s_nop 7
	v_add_f32_e32 v112, v52, v51
	ds_read_b32 v51, v35 offset:1240
	s_waitcnt lgkmcnt(0)
	v_add_f32_e32 v51, v37, v51
	v_add_f32_e32 v113, v53, v51
	ds_read_b32 v51, v34 offset:1240
	s_waitcnt lgkmcnt(0)
	v_add_f32_e32 v51, v36, v51
	v_add_f32_e32 v114, v54, v51
	ds_read_b32 v51, v40 offset:1240
	s_waitcnt lgkmcnt(0)
	v_add_f32_e32 v51, v33, v51
	v_add_f32_e32 v117, v55, v51
	v_add_u32_e32 v51, s50, v32
	v_mad_i32_i24 v51, v51, s5, v103
	ds_read_b128 v[52:55], v51
	ds_read_b128 v[56:59], v51 offset:64
	s_waitcnt lgkmcnt(1)
	v_mfma_f32_16x16x32_bf16 v[52:55], v[52:55], v[4:7], 0
	s_waitcnt lgkmcnt(0)
	v_mfma_f32_16x16x32_bf16 v[52:55], v[56:59], v[0:3], v[52:55]
	ds_read_b32 v56, v41 offset:1364
	s_waitcnt lgkmcnt(0)
	v_add_f32_e32 v56, v42, v56
	s_nop 4
	v_add_f32_e32 v115, v52, v56
	ds_read_b32 v52, v43 offset:1364
	s_waitcnt lgkmcnt(0)
	v_add_f32_e32 v52, v44, v52
	v_add_f32_e32 v116, v53, v52
	ds_read_b32 v52, v45 offset:1364
	s_waitcnt lgkmcnt(0)
	v_add_f32_e32 v52, v46, v52
	v_add_f32_e32 v118, v54, v52
	ds_read_b32 v52, v47 offset:1364
	s_waitcnt lgkmcnt(0)
	v_add_f32_e32 v52, v50, v52
	v_add_f32_e32 v119, v55, v52
	ds_read_b128 v[52:55], v51 offset:576
	ds_read_b128 v[56:59], v51 offset:640
	s_waitcnt lgkmcnt(1)
	v_mfma_f32_16x16x32_bf16 v[52:55], v[52:55], v[4:7], 0
	ds_read_b32 v51, v38 offset:1364
	s_waitcnt lgkmcnt(0)
	v_add_f32_e32 v51, v39, v51
	v_mfma_f32_16x16x32_bf16 v[52:55], v[56:59], v[0:3], v[52:55]
	s_nop 7
	v_add_f32_e32 v120, v52, v51
	ds_read_b32 v51, v35 offset:1364
	s_waitcnt lgkmcnt(0)
	v_add_f32_e32 v51, v37, v51
	v_add_f32_e32 v121, v53, v51
	ds_read_b32 v51, v34 offset:1364
	s_waitcnt lgkmcnt(0)
	v_add_f32_e32 v51, v36, v51
	v_add_f32_e32 v122, v54, v51
	ds_read_b32 v51, v40 offset:1364
	s_waitcnt lgkmcnt(0)
	v_add_f32_e32 v51, v33, v51
	v_add_f32_e32 v125, v55, v51
	v_add_u32_e32 v51, s54, v32
	v_mad_i32_i24 v51, v51, s5, v103
	ds_read_b128 v[52:55], v51
	ds_read_b128 v[56:59], v51 offset:64
	s_waitcnt lgkmcnt(1)
	v_mfma_f32_16x16x32_bf16 v[52:55], v[52:55], v[4:7], 0
	s_waitcnt lgkmcnt(0)
; #define LAS __attribute__((address_space(3)))
; __device__ __forceinline__ f32x4 mfma16(bf16x8 a, bf16x8 b, f32x4 c) { return __builtin_amdgcn_mfma_f32_16x16x32_bf16(a, b, c, 0, 0, 0); }
; template <bool CTXQ>
; __device__ __forceinline__ void attn_super(const bf16_t* QO, bf16_t* OO, const bf16_t* Kb, const bf16_t* VT, const float* rpb, LAS unsigned char* lds, int tid_, int lane_, int wave, int st) {
;     ...
;     for (int grp = G0; grp < 16; ++grp) {
;         const int tb = grp < 8 ? (krl0 + grp) * 64 + ks : 576 + 32 * (grp - 8);
; #pragma unroll
;         for (int T = 0; T < 2; ++T) {
;             const LAS unsigned char* kp = lds + (tb + koff + 4 * T) * AT_PITCH + g * 16;
;             const bf16x8 kf0 = *(const LAS bf16x8*)kp, kf1 = *(const LAS bf16x8*)(kp + 64);
;             f32x4 s = {0.f, 0.f, 0.f, 0.f};
;             s = mfma16(kf0, qf0, s); s = mfma16(kf1, qf1, s);
;             if (grp < 8) {
; #pragma unroll
;                 for (int j = 0; j < 4; ++j) s[j] += bptr[T][j][grp * 31] + madd[T][j];
;             }
;             S[grp][T] = s;
;         }
;         __builtin_amdgcn_sched_barrier(0);
;     }
	v_mfma_f32_16x16x32_bf16 v[52:55], v[56:59], v[0:3], v[52:55]
	ds_read_b32 v56, v41 offset:1488
	s_waitcnt lgkmcnt(0)
	v_add_f32_e32 v56, v42, v56
	s_nop 4
	v_add_f32_e32 v123, v52, v56
	ds_read_b32 v52, v43 offset:1488
	s_waitcnt lgkmcnt(0)
	v_add_f32_e32 v52, v44, v52
	v_add_f32_e32 v124, v53, v52
	ds_read_b32 v52, v45 offset:1488
	s_waitcnt lgkmcnt(0)
	v_add_f32_e32 v52, v46, v52
	v_add_f32_e32 v126, v54, v52
	ds_read_b32 v52, v47 offset:1488
	s_waitcnt lgkmcnt(0)
	v_add_f32_e32 v52, v50, v52
	v_add_f32_e32 v127, v55, v52
	ds_read_b128 v[52:55], v51 offset:576
	ds_read_b128 v[56:59], v51 offset:640
	s_waitcnt lgkmcnt(1)
	v_mfma_f32_16x16x32_bf16 v[52:55], v[52:55], v[4:7], 0
	ds_read_b32 v51, v38 offset:1488
	s_waitcnt lgkmcnt(0)
	v_add_f32_e32 v51, v39, v51
	v_mfma_f32_16x16x32_bf16 v[52:55], v[56:59], v[0:3], v[52:55]
	s_nop 7
	v_add_f32_e32 v128, v52, v51
	ds_read_b32 v51, v35 offset:1488
	s_waitcnt lgkmcnt(0)
	v_add_f32_e32 v51, v37, v51
	v_add_f32_e32 v129, v53, v51
	ds_read_b32 v51, v34 offset:1488
	s_waitcnt lgkmcnt(0)
	v_add_f32_e32 v51, v36, v51
	v_add_f32_e32 v130, v54, v51
	ds_read_b32 v51, v40 offset:1488
	s_waitcnt lgkmcnt(0)
	v_add_f32_e32 v51, v33, v51
	v_add_f32_e32 v133, v55, v51
	v_add_u32_e32 v51, s56, v32
	v_mad_i32_i24 v51, v51, s5, v103
	ds_read_b128 v[52:55], v51
	ds_read_b128 v[56:59], v51 offset:64
	s_waitcnt lgkmcnt(1)
	v_mfma_f32_16x16x32_bf16 v[52:55], v[52:55], v[4:7], 0
	s_waitcnt lgkmcnt(0)
	v_mfma_f32_16x16x32_bf16 v[52:55], v[56:59], v[0:3], v[52:55]
	ds_read_b32 v56, v41 offset:1612
	s_waitcnt lgkmcnt(0)
	v_add_f32_e32 v56, v42, v56
	s_nop 4
	v_add_f32_e32 v131, v52, v56
	ds_read_b32 v52, v43 offset:1612
	s_waitcnt lgkmcnt(0)
	v_add_f32_e32 v52, v44, v52
	v_add_f32_e32 v132, v53, v52
	ds_read_b32 v52, v45 offset:1612
	s_waitcnt lgkmcnt(0)
	v_add_f32_e32 v52, v46, v52
	v_add_f32_e32 v134, v54, v52
	ds_read_b32 v52, v47 offset:1612
	s_waitcnt lgkmcnt(0)
	v_add_f32_e32 v52, v50, v52
	v_add_f32_e32 v135, v55, v52
	ds_read_b128 v[52:55], v51 offset:576
	ds_read_b128 v[56:59], v51 offset:640
	s_waitcnt lgkmcnt(1)
	v_mfma_f32_16x16x32_bf16 v[52:55], v[52:55], v[4:7], 0
	ds_read_b32 v51, v38 offset:1612
	s_waitcnt lgkmcnt(0)
	v_add_f32_e32 v51, v39, v51
	v_mfma_f32_16x16x32_bf16 v[52:55], v[56:59], v[0:3], v[52:55]
	s_nop 7
	v_add_f32_e32 v136, v52, v51
	ds_read_b32 v51, v35 offset:1612
	s_waitcnt lgkmcnt(0)
	v_add_f32_e32 v51, v37, v51
	v_add_f32_e32 v137, v53, v51
	ds_read_b32 v51, v34 offset:1612
	s_waitcnt lgkmcnt(0)
	v_add_f32_e32 v51, v36, v51
	v_add_f32_e32 v138, v54, v51
	ds_read_b32 v51, v40 offset:1612
	s_waitcnt lgkmcnt(0)
	v_add_f32_e32 v51, v33, v51
	v_add_f32_e32 v141, v55, v51
	v_add_u32_e32 v51, s59, v32
	v_mad_i32_i24 v51, v51, s5, v103
	ds_read_b128 v[52:55], v51
	ds_read_b128 v[56:59], v51 offset:64
	ds_read_b32 v41, v41 offset:1736
	s_waitcnt lgkmcnt(2)
	v_mfma_f32_16x16x32_bf16 v[52:55], v[52:55], v[4:7], 0
	s_waitcnt lgkmcnt(0)
	v_add_f32_e32 v41, v42, v41
	v_mfma_f32_16x16x32_bf16 v[52:55], v[56:59], v[0:3], v[52:55]
	s_nop 7
	v_add_f32_e32 v139, v52, v41
	ds_read_b32 v41, v43 offset:1736
	s_waitcnt lgkmcnt(0)
	v_add_f32_e32 v41, v44, v41
	v_add_f32_e32 v140, v53, v41
	ds_read_b32 v41, v45 offset:1736
	s_waitcnt lgkmcnt(0)
	v_add_f32_e32 v41, v46, v41
	v_add_f32_e32 v142, v54, v41
	ds_read_b32 v41, v47 offset:1736
	s_waitcnt lgkmcnt(0)
	v_add_f32_e32 v41, v50, v41
	ds_read_b128 v[42:45], v51 offset:576
	ds_read_b128 v[50:53], v51 offset:640
	s_waitcnt lgkmcnt(1)
	v_mfma_f32_16x16x32_bf16 v[42:45], v[42:45], v[4:7], 0
	ds_read_b32 v38, v38 offset:1736
	ds_read_b32 v35, v35 offset:1736
	ds_read_b32 v34, v34 offset:1736
	s_waitcnt lgkmcnt(3)
	v_mfma_f32_16x16x32_bf16 v[42:45], v[50:53], v[0:3], v[42:45]
	v_add_f32_e32 v143, v55, v41
	s_waitcnt lgkmcnt(2)
	v_add_f32_e32 v38, v39, v38
	s_waitcnt lgkmcnt(1)
	v_add_f32_e32 v35, v37, v35
	s_waitcnt lgkmcnt(0)
	v_add_f32_e32 v34, v36, v34
	s_nop 0
	v_add_f32_e32 v146, v44, v34
	ds_read_b32 v34, v40 offset:1736
	v_add_f32_e32 v144, v42, v38
	v_add_f32_e32 v145, v43, v35
	s_waitcnt lgkmcnt(0)
	v_add_f32_e32 v33, v33, v34
	v_add_f32_e32 v147, v45, v33
	v_mad_u32_u24 v106, v32, s5, v103
	v_add_u32_e32 v32, 0x14400, v106
	ds_read_b128 v[32:35], v32
	v_add_u32_e32 v36, 0x14440, v106
	ds_read_b128 v[36:39], v36
	v_add_u32_e32 v40, 0x14680, v106
	s_waitcnt lgkmcnt(1)
	v_mfma_f32_16x16x32_bf16 v[32:35], v[32:35], v[4:7], 0
	ds_read_b128 v[40:43], v40
	s_waitcnt lgkmcnt(1)
	v_mfma_f32_16x16x32_bf16 v[32:35], v[36:39], v[0:3], v[32:35]
	v_add_u32_e32 v36, 0x14640, v106
	ds_read_b128 v[36:39], v36
	s_waitcnt lgkmcnt(0)
	v_mfma_f32_16x16x32_bf16 v[36:39], v[36:39], v[4:7], 0
	v_mfma_f32_16x16x32_bf16 v[94:97], v[40:43], v[0:3], v[36:39]
	s_nop 6
	v_add_u32_e32 v36, 0x15600, v106
	ds_read_b128 v[36:39], v36
	v_add_u32_e32 v40, 0x15640, v106
	ds_read_b128 v[40:43], v40
	v_add_u32_e32 v44, 0x15880, v106
	s_waitcnt lgkmcnt(1)
	v_mfma_f32_16x16x32_bf16 v[36:39], v[36:39], v[4:7], 0
	ds_read_b128 v[44:47], v44
	s_waitcnt lgkmcnt(1)
	v_mfma_f32_16x16x32_bf16 v[36:39], v[40:43], v[0:3], v[36:39]
	v_add_u32_e32 v40, 0x15840, v106
	ds_read_b128 v[40:43], v40
	s_waitcnt lgkmcnt(0)
	v_mfma_f32_16x16x32_bf16 v[40:43], v[40:43], v[4:7], 0
	v_mfma_f32_16x16x32_bf16 v[90:93], v[44:47], v[0:3], v[40:43]
	s_nop 6
	v_add_u32_e32 v40, 0x16800, v106
	ds_read_b128 v[40:43], v40
	v_add_u32_e32 v44, 0x16840, v106
	ds_read_b128 v[44:47], v44
	v_add_u32_e32 v50, 0x16a80, v106
	s_waitcnt lgkmcnt(1)
	v_mfma_f32_16x16x32_bf16 v[40:43], v[40:43], v[4:7], 0
	ds_read_b128 v[50:53], v50
	s_waitcnt lgkmcnt(1)
	v_mfma_f32_16x16x32_bf16 v[40:43], v[44:47], v[0:3], v[40:43]
	v_add_u32_e32 v44, 0x16a40, v106
	ds_read_b128 v[44:47], v44
	s_waitcnt lgkmcnt(0)
; #define LAS __attribute__((address_space(3)))
; __device__ __forceinline__ f32x4 mfma16(bf16x8 a, bf16x8 b, f32x4 c) { return __builtin_amdgcn_mfma_f32_16x16x32_bf16(a, b, c, 0, 0, 0); }
; template <bool CTXQ>
; __device__ __forceinline__ void attn_super(const bf16_t* QO, bf16_t* OO, const bf16_t* Kb, const bf16_t* VT, const float* rpb, LAS unsigned char* lds, int tid_, int lane_, int wave, int st) {
;     ...
;     for (int grp = G0; grp < 16; ++grp) {
;         const int tb = grp < 8 ? (krl0 + grp) * 64 + ks : 576 + 32 * (grp - 8);
; #pragma unroll
;         for (int T = 0; T < 2; ++T) {
;             const LAS unsigned char* kp = lds + (tb + koff + 4 * T) * AT_PITCH + g * 16;
;             const bf16x8 kf0 = *(const LAS bf16x8*)kp, kf1 = *(const LAS bf16x8*)(kp + 64);
;             f32x4 s = {0.f, 0.f, 0.f, 0.f};
;             s = mfma16(kf0, qf0, s); s = mfma16(kf1, qf1, s);
;             if (grp < 8) {
; #pragma unroll
;                 for (int j = 0; j < 4; ++j) s[j] += bptr[T][j][grp * 31] + madd[T][j];
;             }
;             S[grp][T] = s;
;         }
;         __builtin_amdgcn_sched_barrier(0);
;     }
;     __syncthreads();
;     float mx = -1e30f;
; #pragma unroll
;     for (int grp = G0; grp < 16; ++grp)
; #pragma unroll
;         for (int T = 0; T < 2; ++T) mx = fmaxf(mx, fmaxf(fmaxf(S[grp][T][0], S[grp][T][1]), fmaxf(S[grp][T][2], S[grp][T][3])));
;     mx = fmaxf(mx, __shfl_xor(mx, 16)); mx = fmaxf(mx, __shfl_xor(mx, 32));
	v_mfma_f32_16x16x32_bf16 v[44:47], v[44:47], v[4:7], 0
	v_mfma_f32_16x16x32_bf16 v[86:89], v[50:53], v[0:3], v[44:47]
	s_nop 6
	v_add_u32_e32 v44, 0x17a00, v106
	ds_read_b128 v[44:47], v44
	v_add_u32_e32 v50, 0x17a40, v106
	ds_read_b128 v[50:53], v50
	v_add_u32_e32 v54, 0x17c80, v106
	s_waitcnt lgkmcnt(1)
	v_mfma_f32_16x16x32_bf16 v[44:47], v[44:47], v[4:7], 0
	ds_read_b128 v[54:57], v54
	s_waitcnt lgkmcnt(1)
	v_mfma_f32_16x16x32_bf16 v[44:47], v[50:53], v[0:3], v[44:47]
	v_add_u32_e32 v50, 0x17c40, v106
	ds_read_b128 v[50:53], v50
	s_waitcnt lgkmcnt(0)
	v_mfma_f32_16x16x32_bf16 v[50:53], v[50:53], v[4:7], 0
	v_mfma_f32_16x16x32_bf16 v[82:85], v[54:57], v[0:3], v[50:53]
	s_nop 6
	v_add_u32_e32 v50, 0x18c00, v106
	ds_read_b128 v[50:53], v50
	v_add_u32_e32 v54, 0x18c40, v106
	ds_read_b128 v[54:57], v54
	v_add_u32_e32 v58, 0x18e80, v106
	s_waitcnt lgkmcnt(1)
	v_mfma_f32_16x16x32_bf16 v[50:53], v[50:53], v[4:7], 0
	ds_read_b128 v[58:61], v58
	s_waitcnt lgkmcnt(1)
	v_mfma_f32_16x16x32_bf16 v[50:53], v[54:57], v[0:3], v[50:53]
	v_add_u32_e32 v54, 0x18e40, v106
	ds_read_b128 v[54:57], v54
	s_waitcnt lgkmcnt(0)
	v_mfma_f32_16x16x32_bf16 v[54:57], v[54:57], v[4:7], 0
	v_mfma_f32_16x16x32_bf16 v[78:81], v[58:61], v[0:3], v[54:57]
	s_nop 6
	v_add_u32_e32 v54, 0x19e00, v106
	ds_read_b128 v[54:57], v54
	v_add_u32_e32 v58, 0x19e40, v106
	ds_read_b128 v[58:61], v58
	v_add_u32_e32 v62, 0x1a080, v106
	s_waitcnt lgkmcnt(1)
	v_mfma_f32_16x16x32_bf16 v[54:57], v[54:57], v[4:7], 0
	ds_read_b128 v[62:65], v62
	s_waitcnt lgkmcnt(1)
	v_mfma_f32_16x16x32_bf16 v[54:57], v[58:61], v[0:3], v[54:57]
	v_add_u32_e32 v58, 0x1a040, v106
	ds_read_b128 v[58:61], v58
	s_waitcnt lgkmcnt(0)
	v_mfma_f32_16x16x32_bf16 v[58:61], v[58:61], v[4:7], 0
	v_mfma_f32_16x16x32_bf16 v[70:73], v[62:65], v[0:3], v[58:61]
	s_nop 6
	v_add_u32_e32 v58, 0x1b000, v106
	ds_read_b128 v[58:61], v58
	v_add_u32_e32 v62, 0x1b040, v106
	ds_read_b128 v[62:65], v62
	v_add_u32_e32 v66, 0x1b280, v106
	s_waitcnt lgkmcnt(1)
	v_mfma_f32_16x16x32_bf16 v[58:61], v[58:61], v[4:7], 0
	ds_read_b128 v[66:69], v66
	s_waitcnt lgkmcnt(1)
	v_mfma_f32_16x16x32_bf16 v[58:61], v[62:65], v[0:3], v[58:61]
	v_add_u32_e32 v62, 0x1b240, v106
	ds_read_b128 v[62:65], v62
	s_waitcnt lgkmcnt(0)
	v_mfma_f32_16x16x32_bf16 v[62:65], v[62:65], v[4:7], 0
	v_mfma_f32_16x16x32_bf16 v[62:65], v[66:69], v[0:3], v[62:65]
	v_add_u32_e32 v66, 0x1c200, v106
	v_add_u32_e32 v74, 0x1c440, v106
	ds_read_b128 v[66:69], v66
	ds_read_b128 v[74:77], v74
	v_add_u32_e32 v107, 0x1c240, v106
	v_add_u32_e32 v106, 0x1c480, v106
	s_waitcnt lgkmcnt(1)
	v_mfma_f32_16x16x32_bf16 v[66:69], v[66:69], v[4:7], 0
	s_waitcnt lgkmcnt(0)
	v_mfma_f32_16x16x32_bf16 v[4:7], v[74:77], v[4:7], 0
	ds_read_b128 v[74:77], v107
	s_waitcnt lgkmcnt(0)
	v_mfma_f32_16x16x32_bf16 v[74:77], v[74:77], v[0:3], v[66:69]
	s_nop 2
	ds_read_b128 v[66:69], v106
	s_waitcnt lgkmcnt(0)
	v_mfma_f32_16x16x32_bf16 v[66:69], v[66:69], v[0:3], v[4:7]
	v_max_f32_e32 v0, v17, v16
	v_max_f32_e32 v1, v11, v10
	v_max3_f32 v0, v19, v18, v0
	v_max3_f32 v1, v15, v13, v1
	s_mov_b32 s2, 0xf149f2ca
	v_max3_f32 v0, v0, s2, v1
	v_max_f32_e32 v1, v12, v14
	v_max_f32_e32 v2, v22, v25
	v_max3_f32 v1, v8, v9, v1
	v_max3_f32 v2, v20, v21, v2
	v_max3_f32 v0, v0, v1, v2
	v_max_f32_e32 v1, v26, v27
	v_max_f32_e32 v2, v30, v109
	v_max3_f32 v1, v23, v24, v1
	v_max3_f32 v2, v28, v29, v2
	v_max3_f32 v0, v0, v1, v2
	v_max_f32_e32 v1, v110, v111
	v_max_f32_e32 v2, v114, v117
	v_max3_f32 v1, v31, v108, v1
	v_max3_f32 v2, v112, v113, v2
	v_max3_f32 v0, v0, v1, v2
	v_max_f32_e32 v1, v118, v119
	v_max_f32_e32 v2, v122, v125
	v_max3_f32 v1, v115, v116, v1
	v_max3_f32 v2, v120, v121, v2
	v_max3_f32 v0, v0, v1, v2
	v_max_f32_e32 v1, v126, v127
	v_max_f32_e32 v2, v130, v133
	v_max3_f32 v1, v123, v124, v1
	v_max3_f32 v2, v128, v129, v2
	v_max3_f32 v0, v0, v1, v2
	v_max_f32_e32 v1, v134, v135
	v_max_f32_e32 v2, v138, v141
	v_max3_f32 v1, v131, v132, v1
	v_max3_f32 v2, v136, v137, v2
	v_max3_f32 v0, v0, v1, v2
	v_max_f32_e32 v1, v142, v143
	v_max_f32_e32 v2, v146, v147
	v_max3_f32 v1, v139, v140, v1
	v_max3_f32 v2, v144, v145, v2
	v_max3_f32 v0, v0, v1, v2
	v_max_f32_e32 v1, v35, v35
	v_max_f32_e32 v2, v34, v34
	v_max_f32_e32 v1, v2, v1
	v_max_f32_e32 v2, v97, v97
	v_max_f32_e32 v3, v96, v96
	v_max_f32_e32 v2, v3, v2
	v_max3_f32 v1, v32, v33, v1
	v_max3_f32 v2, v94, v95, v2
	v_max3_f32 v0, v0, v1, v2
	v_max_f32_e32 v1, v39, v39
	v_max_f32_e32 v2, v38, v38
	v_max_f32_e32 v1, v2, v1
	v_max_f32_e32 v2, v93, v93
	v_max_f32_e32 v3, v92, v92
	v_max_f32_e32 v2, v3, v2
	v_max3_f32 v1, v36, v37, v1
	v_max3_f32 v2, v90, v91, v2
	v_max3_f32 v0, v0, v1, v2
	v_max_f32_e32 v1, v43, v43
	v_max_f32_e32 v2, v42, v42
	v_max_f32_e32 v1, v2, v1
	v_max_f32_e32 v2, v89, v89
	v_max_f32_e32 v3, v88, v88
	v_max_f32_e32 v2, v3, v2
	v_max3_f32 v1, v40, v41, v1
	v_max3_f32 v2, v86, v87, v2
	v_max3_f32 v0, v0, v1, v2
	v_max_f32_e32 v1, v47, v47
	v_max_f32_e32 v2, v46, v46
	v_max_f32_e32 v1, v2, v1
	v_max_f32_e32 v2, v85, v85
	v_max_f32_e32 v3, v84, v84
	v_max_f32_e32 v2, v3, v2
	v_max3_f32 v1, v44, v45, v1
	v_max3_f32 v2, v82, v83, v2
	v_max3_f32 v0, v0, v1, v2
	v_max_f32_e32 v1, v53, v53
	v_max_f32_e32 v2, v52, v52
	v_max_f32_e32 v1, v2, v1
	v_max_f32_e32 v2, v81, v81
	v_max_f32_e32 v3, v80, v80
	v_max_f32_e32 v2, v3, v2
	v_max3_f32 v1, v50, v51, v1
	v_max3_f32 v2, v78, v79, v2
	v_max3_f32 v0, v0, v1, v2
	v_max_f32_e32 v1, v57, v57
	v_max_f32_e32 v2, v56, v56
	v_max_f32_e32 v1, v2, v1
	v_max_f32_e32 v2, v73, v73
	v_max_f32_e32 v3, v72, v72
	v_max_f32_e32 v2, v3, v2
	v_max3_f32 v1, v54, v55, v1
	v_max3_f32 v2, v70, v71, v2
	v_max3_f32 v0, v0, v1, v2
	v_max_f32_e32 v1, v61, v61
	v_max_f32_e32 v2, v60, v60
	v_max_f32_e32 v1, v2, v1
	v_max_f32_e32 v2, v65, v65
	v_max_f32_e32 v3, v64, v64
	v_max_f32_e32 v2, v3, v2
	v_max3_f32 v1, v58, v59, v1
	v_max3_f32 v2, v62, v63, v2
	v_max3_f32 v0, v0, v1, v2
	v_max_f32_e32 v1, v77, v77
	v_max_f32_e32 v2, v76, v76
	v_max_f32_e32 v1, v2, v1
	v_max_f32_e32 v2, v69, v69
	v_max_f32_e32 v3, v68, v68
	v_max_f32_e32 v2, v3, v2
	v_max3_f32 v1, v74, v75, v1
	v_max3_f32 v2, v66, v67, v2
	v_max3_f32 v0, v0, v1, v2
	v_xor_b32_e32 v1, 16, v222
	v_cmp_lt_i32_e32 vcc, v1, v227
	s_barrier
; __device__ __forceinline__ unsigned pk2(float lo, float hi) { unsigned r; asm("v_cvt_pk_bf16_f32 %0, %1, %2" : "=v"(r) : "v"(lo), "v"(hi)); return r; }
; template <bool CTXQ>
; __device__ __forceinline__ void attn_super(const bf16_t* QO, bf16_t* OO, const bf16_t* Kb, const bf16_t* VT, const float* rpb, LAS unsigned char* lds, int tid_, int lane_, int wave, int st) {
;     ...
;     mx = fmaxf(mx, __shfl_xor(mx, 16)); mx = fmaxf(mx, __shfl_xor(mx, 32));
;     float sum = 0.f;
;     u32x4 P[16];
; #pragma unroll
;     for (int grp = G0; grp < 16; ++grp) {
;         float p[8];
; #pragma unroll
;         for (int T = 0; T < 2; ++T)
; #pragma unroll
;             for (int j = 0; j < 4; ++j) { p[4 * T + j] = __builtin_amdgcn_exp2f(S[grp][T][j] - mx); sum += p[4 * T + j]; }
;         P[grp].x = pk2(p[0], p[1]); P[grp].y = pk2(p[2], p[3]); P[grp].z = pk2(p[4], p[5]); P[grp].w = pk2(p[6], p[7]);
;         __builtin_amdgcn_sched_barrier(0);
;     }
	s_nop 0
	v_cndmask_b32_e32 v1, v222, v1, vcc
	v_lshlrev_b32_e32 v106, 2, v1
	ds_bpermute_b32 v1, v106, v0
	v_cmp_lt_i32_e32 vcc, v226, v227
	s_waitcnt lgkmcnt(0)
	v_max_f32_e32 v1, v1, v1
	v_max_f32_e32 v0, v0, v1
	v_cndmask_b32_e32 v1, v222, v226, vcc
	v_lshlrev_b32_e32 v107, 2, v1
	ds_bpermute_b32 v1, v107, v0
	s_waitcnt lgkmcnt(0)
	v_max_f32_e32 v1, v1, v1
	v_max_f32_e32 v148, v0, v1
	v_sub_f32_e32 v0, v19, v148
	v_exp_f32_e32 v0, v0
	v_sub_f32_e32 v1, v18, v148
	v_exp_f32_e32 v1, v1
	v_sub_f32_e32 v2, v17, v148
	v_exp_f32_e32 v2, v2
	v_sub_f32_e32 v3, v16, v148
	v_exp_f32_e32 v3, v3
	v_sub_f32_e32 v5, v15, v148
	v_add_f32_e32 v4, 0, v0
	v_exp_f32_e32 v6, v5
	v_sub_f32_e32 v5, v13, v148
	v_add_f32_e32 v4, v1, v4
	v_exp_f32_e32 v7, v5
	v_sub_f32_e32 v5, v11, v148
	v_add_f32_e32 v4, v2, v4
	v_exp_f32_e32 v11, v5
	v_sub_f32_e32 v5, v10, v148
	v_add_f32_e32 v4, v3, v4
	v_exp_f32_e32 v10, v5
	v_add_f32_e32 v4, v6, v4
	v_add_f32_e32 v4, v7, v4
	v_add_f32_e32 v4, v11, v4
	v_add_f32_e32 v13, v10, v4
	v_cvt_pk_bf16_f32 v4, v0, v1
	v_cvt_pk_bf16_f32 v5, v2, v3
	v_cvt_pk_bf16_f32 v6, v6, v7
	v_cvt_pk_bf16_f32 v7, v11, v10
	v_sub_f32_e32 v0, v8, v148
	v_exp_f32_e32 v0, v0
	v_sub_f32_e32 v1, v9, v148
	v_exp_f32_e32 v1, v1
	v_sub_f32_e32 v2, v12, v148
	v_exp_f32_e32 v2, v2
	v_sub_f32_e32 v3, v14, v148
	v_exp_f32_e32 v3, v3
	v_sub_f32_e32 v9, v20, v148
	v_add_f32_e32 v8, v0, v13
	v_exp_f32_e32 v9, v9
	v_sub_f32_e32 v10, v21, v148
	v_add_f32_e32 v8, v1, v8
	v_exp_f32_e32 v10, v10
	v_sub_f32_e32 v11, v22, v148
	v_add_f32_e32 v8, v2, v8
	v_exp_f32_e32 v11, v11
	v_sub_f32_e32 v12, v25, v148
	v_add_f32_e32 v8, v3, v8
	v_exp_f32_e32 v12, v12
	v_add_f32_e32 v8, v9, v8
	v_add_f32_e32 v8, v10, v8
	v_add_f32_e32 v8, v11, v8
	v_add_f32_e32 v8, v12, v8
	v_cvt_pk_bf16_f32 v0, v0, v1
	v_cvt_pk_bf16_f32 v1, v2, v3
	v_cvt_pk_bf16_f32 v2, v9, v10
	v_cvt_pk_bf16_f32 v3, v11, v12
	v_sub_f32_e32 v9, v23, v148
	v_exp_f32_e32 v9, v9
	v_sub_f32_e32 v10, v24, v148
	v_exp_f32_e32 v10, v10
	v_sub_f32_e32 v11, v26, v148
	v_exp_f32_e32 v11, v11
	v_sub_f32_e32 v12, v27, v148
	v_exp_f32_e32 v12, v12
	v_sub_f32_e32 v13, v28, v148
	v_add_f32_e32 v8, v9, v8
	v_exp_f32_e32 v13, v13
	v_sub_f32_e32 v14, v29, v148
	v_add_f32_e32 v8, v10, v8
	v_exp_f32_e32 v14, v14
	v_sub_f32_e32 v15, v30, v148
	v_add_f32_e32 v8, v11, v8
	v_exp_f32_e32 v15, v15
	v_sub_f32_e32 v16, v109, v148
	v_add_f32_e32 v8, v12, v8
	v_exp_f32_e32 v16, v16
	v_add_f32_e32 v8, v13, v8
	v_add_f32_e32 v8, v14, v8
	v_add_f32_e32 v8, v15, v8
	v_add_f32_e32 v17, v16, v8
	v_cvt_pk_bf16_f32 v8, v9, v10
	v_cvt_pk_bf16_f32 v9, v11, v12
	v_cvt_pk_bf16_f32 v10, v13, v14
	v_cvt_pk_bf16_f32 v11, v15, v16
	v_sub_f32_e32 v12, v31, v148
	v_exp_f32_e32 v12, v12
	v_sub_f32_e32 v13, v108, v148
	v_exp_f32_e32 v13, v13
	v_sub_f32_e32 v14, v110, v148
	v_exp_f32_e32 v14, v14
	v_sub_f32_e32 v15, v111, v148
	v_exp_f32_e32 v15, v15
	v_add_f32_e32 v16, v12, v17
	v_sub_f32_e32 v17, v112, v148
	v_exp_f32_e32 v17, v17
	v_sub_f32_e32 v18, v113, v148
	v_add_f32_e32 v16, v13, v16
	v_exp_f32_e32 v18, v18
	v_sub_f32_e32 v19, v114, v148
	v_add_f32_e32 v16, v14, v16
	v_exp_f32_e32 v19, v19
	v_sub_f32_e32 v20, v117, v148
	v_add_f32_e32 v16, v15, v16
	v_exp_f32_e32 v20, v20
	v_add_f32_e32 v16, v17, v16
	v_add_f32_e32 v16, v18, v16
	v_add_f32_e32 v16, v19, v16
	v_add_f32_e32 v16, v20, v16
	v_cvt_pk_bf16_f32 v12, v12, v13
	v_cvt_pk_bf16_f32 v13, v14, v15
	v_cvt_pk_bf16_f32 v14, v17, v18
	v_cvt_pk_bf16_f32 v15, v19, v20
	v_sub_f32_e32 v17, v115, v148
	v_exp_f32_e32 v17, v17
	v_sub_f32_e32 v18, v116, v148
	v_exp_f32_e32 v18, v18
	v_sub_f32_e32 v19, v118, v148
	v_exp_f32_e32 v19, v19
	v_sub_f32_e32 v20, v119, v148
	v_exp_f32_e32 v20, v20
	v_sub_f32_e32 v21, v120, v148
	v_add_f32_e32 v16, v17, v16
	v_exp_f32_e32 v21, v21
	v_sub_f32_e32 v22, v121, v148
	v_add_f32_e32 v16, v18, v16
	v_exp_f32_e32 v22, v22
	v_sub_f32_e32 v23, v122, v148
	v_add_f32_e32 v16, v19, v16
	v_exp_f32_e32 v23, v23
	v_sub_f32_e32 v24, v125, v148
	v_add_f32_e32 v16, v20, v16
	v_exp_f32_e32 v24, v24
	v_add_f32_e32 v16, v21, v16
	v_add_f32_e32 v16, v22, v16
	v_add_f32_e32 v16, v23, v16
	v_add_f32_e32 v25, v24, v16
	v_cvt_pk_bf16_f32 v16, v17, v18
	v_cvt_pk_bf16_f32 v17, v19, v20
	v_cvt_pk_bf16_f32 v18, v21, v22
	v_cvt_pk_bf16_f32 v19, v23, v24
	v_sub_f32_e32 v20, v123, v148
	v_exp_f32_e32 v20, v20
	v_sub_f32_e32 v21, v124, v148
	v_exp_f32_e32 v21, v21
	v_sub_f32_e32 v22, v126, v148
	v_exp_f32_e32 v22, v22
	v_sub_f32_e32 v23, v127, v148
	v_exp_f32_e32 v23, v23
	v_add_f32_e32 v24, v20, v25
	v_sub_f32_e32 v25, v128, v148
	v_exp_f32_e32 v25, v25
	v_sub_f32_e32 v26, v129, v148
	v_add_f32_e32 v24, v21, v24
	v_exp_f32_e32 v26, v26
	v_sub_f32_e32 v27, v130, v148
	v_add_f32_e32 v24, v22, v24
	v_exp_f32_e32 v27, v27
	v_sub_f32_e32 v28, v133, v148
	v_add_f32_e32 v24, v23, v24
	v_exp_f32_e32 v28, v28
	v_add_f32_e32 v24, v25, v24
	v_add_f32_e32 v24, v26, v24
	v_add_f32_e32 v24, v27, v24
	v_add_f32_e32 v24, v28, v24
	v_cvt_pk_bf16_f32 v20, v20, v21
	v_cvt_pk_bf16_f32 v21, v22, v23
	v_cvt_pk_bf16_f32 v22, v25, v26
	v_cvt_pk_bf16_f32 v23, v27, v28
	v_sub_f32_e32 v25, v131, v148
	v_exp_f32_e32 v25, v25
	v_sub_f32_e32 v26, v132, v148
	v_exp_f32_e32 v26, v26
	v_sub_f32_e32 v27, v134, v148
	v_exp_f32_e32 v27, v27
	v_sub_f32_e32 v28, v135, v148
	v_exp_f32_e32 v28, v28
	v_sub_f32_e32 v29, v136, v148
	v_add_f32_e32 v24, v25, v24
	v_exp_f32_e32 v29, v29
	v_sub_f32_e32 v30, v137, v148
	v_add_f32_e32 v24, v26, v24
	v_exp_f32_e32 v30, v30
	v_sub_f32_e32 v31, v138, v148
	v_add_f32_e32 v24, v27, v24
	v_exp_f32_e32 v31, v31
	v_sub_f32_e32 v108, v141, v148
	v_add_f32_e32 v24, v28, v24
	v_exp_f32_e32 v108, v108
; __device__ __forceinline__ unsigned pk2(float lo, float hi) { unsigned r; asm("v_cvt_pk_bf16_f32 %0, %1, %2" : "=v"(r) : "v"(lo), "v"(hi)); return r; }
; template <bool CTXQ>
; __device__ __forceinline__ void attn_super(const bf16_t* QO, bf16_t* OO, const bf16_t* Kb, const bf16_t* VT, const float* rpb, LAS unsigned char* lds, int tid_, int lane_, int wave, int st) {
;     ...
; #pragma unroll
;     for (int grp = G0; grp < 16; ++grp) {
;         float p[8];
; #pragma unroll
;         for (int T = 0; T < 2; ++T)
; #pragma unroll
;             for (int j = 0; j < 4; ++j) { p[4 * T + j] = __builtin_amdgcn_exp2f(S[grp][T][j] - mx); sum += p[4 * T + j]; }
;         P[grp].x = pk2(p[0], p[1]); P[grp].y = pk2(p[2], p[3]); P[grp].z = pk2(p[4], p[5]); P[grp].w = pk2(p[6], p[7]);
;         __builtin_amdgcn_sched_barrier(0);
;     }
	v_add_f32_e32 v24, v29, v24
	v_add_f32_e32 v24, v30, v24
	v_add_f32_e32 v24, v31, v24
	v_add_f32_e32 v109, v108, v24
	v_cvt_pk_bf16_f32 v24, v25, v26
	v_cvt_pk_bf16_f32 v25, v27, v28
	v_cvt_pk_bf16_f32 v26, v29, v30
	v_cvt_pk_bf16_f32 v27, v31, v108
	v_sub_f32_e32 v28, v139, v148
	v_exp_f32_e32 v28, v28
	v_sub_f32_e32 v29, v140, v148
	v_exp_f32_e32 v29, v29
	v_sub_f32_e32 v30, v142, v148
	v_exp_f32_e32 v30, v30
	v_sub_f32_e32 v31, v143, v148
	v_exp_f32_e32 v31, v31
	v_add_f32_e32 v108, v28, v109
	v_sub_f32_e32 v109, v144, v148
	v_exp_f32_e32 v109, v109
	v_sub_f32_e32 v110, v145, v148
	v_add_f32_e32 v108, v29, v108
	v_exp_f32_e32 v110, v110
	v_sub_f32_e32 v111, v146, v148
	v_add_f32_e32 v108, v30, v108
	v_exp_f32_e32 v111, v111
	v_sub_f32_e32 v112, v147, v148
	v_add_f32_e32 v108, v31, v108
	v_exp_f32_e32 v112, v112
	v_add_f32_e32 v108, v109, v108
	v_add_f32_e32 v108, v110, v108
	v_add_f32_e32 v108, v111, v108
	v_add_f32_e32 v108, v112, v108
	v_cvt_pk_bf16_f32 v28, v28, v29
	v_cvt_pk_bf16_f32 v29, v30, v31
	v_cvt_pk_bf16_f32 v30, v109, v110
	v_cvt_pk_bf16_f32 v31, v111, v112
	v_sub_f32_e32 v32, v32, v148
	v_exp_f32_e32 v32, v32
	v_sub_f32_e32 v33, v33, v148
	v_exp_f32_e32 v33, v33
	v_sub_f32_e32 v34, v34, v148
	v_exp_f32_e32 v34, v34
	v_sub_f32_e32 v35, v35, v148
	v_exp_f32_e32 v35, v35
	v_sub_f32_e32 v94, v94, v148
	v_add_f32_e32 v108, v32, v108
	v_exp_f32_e32 v94, v94
	v_sub_f32_e32 v95, v95, v148
	v_add_f32_e32 v108, v33, v108
	v_exp_f32_e32 v95, v95
	v_sub_f32_e32 v96, v96, v148
	v_add_f32_e32 v108, v34, v108
	v_exp_f32_e32 v96, v96
	v_sub_f32_e32 v97, v97, v148
	v_add_f32_e32 v108, v35, v108
	v_exp_f32_e32 v97, v97
	v_add_f32_e32 v108, v94, v108
	v_add_f32_e32 v108, v95, v108
	v_add_f32_e32 v108, v96, v108
	v_add_f32_e32 v108, v97, v108
	v_cvt_pk_bf16_f32 v32, v32, v33
	v_cvt_pk_bf16_f32 v33, v34, v35
	v_cvt_pk_bf16_f32 v34, v94, v95
	v_cvt_pk_bf16_f32 v35, v96, v97
	v_sub_f32_e32 v36, v36, v148
	v_exp_f32_e32 v36, v36
	v_sub_f32_e32 v37, v37, v148
	v_exp_f32_e32 v37, v37
	v_sub_f32_e32 v38, v38, v148
	v_exp_f32_e32 v38, v38
	v_sub_f32_e32 v39, v39, v148
	v_exp_f32_e32 v39, v39
	v_sub_f32_e32 v90, v90, v148
	v_add_f32_e32 v94, v36, v108
	v_exp_f32_e32 v90, v90
	v_sub_f32_e32 v91, v91, v148
	v_add_f32_e32 v94, v37, v94
	v_exp_f32_e32 v91, v91
	v_sub_f32_e32 v92, v92, v148
	v_add_f32_e32 v94, v38, v94
	v_exp_f32_e32 v92, v92
	v_sub_f32_e32 v93, v93, v148
	v_add_f32_e32 v94, v39, v94
	v_exp_f32_e32 v93, v93
	v_add_f32_e32 v94, v90, v94
	v_add_f32_e32 v94, v91, v94
	v_add_f32_e32 v94, v92, v94
	v_add_f32_e32 v94, v93, v94
	v_cvt_pk_bf16_f32 v36, v36, v37
	v_cvt_pk_bf16_f32 v37, v38, v39
	v_cvt_pk_bf16_f32 v38, v90, v91
	v_cvt_pk_bf16_f32 v39, v92, v93
	v_sub_f32_e32 v40, v40, v148
	v_exp_f32_e32 v40, v40
	v_sub_f32_e32 v41, v41, v148
	v_exp_f32_e32 v41, v41
	v_sub_f32_e32 v42, v42, v148
	v_exp_f32_e32 v42, v42
	v_sub_f32_e32 v43, v43, v148
	v_exp_f32_e32 v43, v43
	v_sub_f32_e32 v86, v86, v148
	v_add_f32_e32 v90, v40, v94
	v_exp_f32_e32 v86, v86
	v_sub_f32_e32 v87, v87, v148
	v_add_f32_e32 v90, v41, v90
	v_exp_f32_e32 v87, v87
	v_sub_f32_e32 v88, v88, v148
	v_add_f32_e32 v90, v42, v90
	v_exp_f32_e32 v88, v88
	v_sub_f32_e32 v89, v89, v148
	v_add_f32_e32 v90, v43, v90
	v_exp_f32_e32 v89, v89
	v_add_f32_e32 v90, v86, v90
	v_add_f32_e32 v90, v87, v90
	v_add_f32_e32 v90, v88, v90
	v_add_f32_e32 v90, v89, v90
	v_cvt_pk_bf16_f32 v40, v40, v41
	v_cvt_pk_bf16_f32 v41, v42, v43
	v_cvt_pk_bf16_f32 v42, v86, v87
	v_cvt_pk_bf16_f32 v43, v88, v89
	v_sub_f32_e32 v44, v44, v148
	v_exp_f32_e32 v44, v44
	v_sub_f32_e32 v45, v45, v148
	v_exp_f32_e32 v45, v45
	v_sub_f32_e32 v46, v46, v148
	v_exp_f32_e32 v46, v46
	v_sub_f32_e32 v47, v47, v148
	v_exp_f32_e32 v47, v47
	v_sub_f32_e32 v82, v82, v148
	v_add_f32_e32 v86, v44, v90
	v_exp_f32_e32 v82, v82
	v_sub_f32_e32 v83, v83, v148
	v_add_f32_e32 v86, v45, v86
	v_exp_f32_e32 v83, v83
	v_sub_f32_e32 v84, v84, v148
	v_add_f32_e32 v86, v46, v86
	v_exp_f32_e32 v84, v84
	v_sub_f32_e32 v85, v85, v148
	v_add_f32_e32 v86, v47, v86
	v_exp_f32_e32 v85, v85
	v_add_f32_e32 v86, v82, v86
	v_add_f32_e32 v86, v83, v86
	v_add_f32_e32 v86, v84, v86
	v_add_f32_e32 v86, v85, v86
	v_cvt_pk_bf16_f32 v44, v44, v45
	v_cvt_pk_bf16_f32 v45, v46, v47
	v_cvt_pk_bf16_f32 v46, v82, v83
	v_cvt_pk_bf16_f32 v47, v84, v85
	v_sub_f32_e32 v50, v50, v148
	v_exp_f32_e32 v50, v50
	v_sub_f32_e32 v51, v51, v148
	v_exp_f32_e32 v51, v51
	v_sub_f32_e32 v52, v52, v148
	v_exp_f32_e32 v52, v52
	v_sub_f32_e32 v53, v53, v148
	v_exp_f32_e32 v53, v53
	v_sub_f32_e32 v78, v78, v148
	v_add_f32_e32 v82, v50, v86
	v_exp_f32_e32 v78, v78
	v_sub_f32_e32 v79, v79, v148
	v_add_f32_e32 v82, v51, v82
	v_exp_f32_e32 v79, v79
	v_sub_f32_e32 v80, v80, v148
	v_add_f32_e32 v82, v52, v82
	v_exp_f32_e32 v80, v80
	v_sub_f32_e32 v81, v81, v148
	v_add_f32_e32 v82, v53, v82
	v_exp_f32_e32 v81, v81
	v_add_f32_e32 v82, v78, v82
	v_add_f32_e32 v82, v79, v82
	v_add_f32_e32 v82, v80, v82
	v_add_f32_e32 v82, v81, v82
	v_cvt_pk_bf16_f32 v50, v50, v51
	v_cvt_pk_bf16_f32 v51, v52, v53
	v_cvt_pk_bf16_f32 v52, v78, v79
	v_cvt_pk_bf16_f32 v53, v80, v81
	v_sub_f32_e32 v54, v54, v148
	v_exp_f32_e32 v54, v54
	v_sub_f32_e32 v55, v55, v148
	v_exp_f32_e32 v55, v55
	v_sub_f32_e32 v56, v56, v148
	v_exp_f32_e32 v56, v56
	v_sub_f32_e32 v57, v57, v148
	v_exp_f32_e32 v57, v57
	v_sub_f32_e32 v70, v70, v148
	v_add_f32_e32 v78, v54, v82
	v_exp_f32_e32 v70, v70
	v_sub_f32_e32 v71, v71, v148
	v_add_f32_e32 v78, v55, v78
	v_exp_f32_e32 v71, v71
	v_sub_f32_e32 v72, v72, v148
	v_add_f32_e32 v78, v56, v78
	v_exp_f32_e32 v72, v72
	v_sub_f32_e32 v73, v73, v148
	v_add_f32_e32 v78, v57, v78
	v_exp_f32_e32 v73, v73
; #define LAS __attribute__((address_space(3)))
; template <bool CTXQ>
; __device__ __forceinline__ void attn_super(const bf16_t* QO, bf16_t* OO, const bf16_t* Kb, const bf16_t* VT, const float* rpb, LAS unsigned char* lds, int tid_, int lane_, int wave, int st) {
;     ...
;     sum += __shfl_xor(sum, 16); sum += __shfl_xor(sum, 32);
; #pragma unroll
;     for (int i = I0; i < 13; ++i) { const int d = (tid >> 3) & 63, cc = tid & 7;
;         const size_t tokb = i < 9 ? (size_t)b * SEQ + (kbase + i) * 64 : (size_t)ML + b * CTXL + (i - 9) * 64;
;         stg[i] = *(const u32x4*)(VT + (size_t)(h * 64 + d) * MT + tokb + cc * 8); }
; #pragma unroll
;     for (int i = I0; i < 13; ++i) { const int d = (tid >> 3) & 63, cc = tid & 7; *(LAS u32x4*)(lds + (i * 64 + d) * AT_PITCH + cc * 16) = stg[i]; }
;     __syncthreads();
	v_add_f32_e32 v78, v70, v78
	v_add_f32_e32 v78, v71, v78
	v_add_f32_e32 v78, v72, v78
	v_add_f32_e32 v78, v73, v78
	v_cvt_pk_bf16_f32 v54, v54, v55
	v_cvt_pk_bf16_f32 v55, v56, v57
	v_cvt_pk_bf16_f32 v56, v70, v71
	v_cvt_pk_bf16_f32 v57, v72, v73
	v_sub_f32_e32 v58, v58, v148
	v_exp_f32_e32 v58, v58
	v_sub_f32_e32 v59, v59, v148
	v_exp_f32_e32 v59, v59
	v_sub_f32_e32 v60, v60, v148
	v_exp_f32_e32 v60, v60
	v_sub_f32_e32 v61, v61, v148
	v_exp_f32_e32 v61, v61
	v_sub_f32_e32 v62, v62, v148
	v_add_f32_e32 v70, v58, v78
	v_exp_f32_e32 v71, v62
	v_sub_f32_e32 v62, v63, v148
	v_add_f32_e32 v70, v59, v70
	v_exp_f32_e32 v72, v62
	v_sub_f32_e32 v62, v64, v148
	v_add_f32_e32 v70, v60, v70
	v_exp_f32_e32 v73, v62
	v_sub_f32_e32 v62, v65, v148
	v_add_f32_e32 v70, v61, v70
	v_exp_f32_e32 v65, v62
	v_add_f32_e32 v62, v71, v70
	v_add_f32_e32 v62, v72, v62
	v_add_f32_e32 v62, v73, v62
	v_add_f32_e32 v70, v65, v62
	v_cvt_pk_bf16_f32 v62, v58, v59
	v_cvt_pk_bf16_f32 v63, v60, v61
	v_cvt_pk_bf16_f32 v64, v71, v72
	v_cvt_pk_bf16_f32 v65, v73, v65
	v_sub_f32_e32 v58, v74, v148
	v_exp_f32_e32 v58, v58
	v_sub_f32_e32 v59, v75, v148
	v_exp_f32_e32 v59, v59
	v_sub_f32_e32 v60, v76, v148
	v_exp_f32_e32 v60, v60
	v_sub_f32_e32 v61, v77, v148
	v_exp_f32_e32 v61, v61
	v_sub_f32_e32 v66, v66, v148
	v_add_f32_e32 v70, v58, v70
	v_exp_f32_e32 v66, v66
	v_sub_f32_e32 v67, v67, v148
	v_add_f32_e32 v70, v59, v70
	v_exp_f32_e32 v67, v67
	v_sub_f32_e32 v68, v68, v148
	v_add_f32_e32 v70, v60, v70
	v_exp_f32_e32 v68, v68
	v_sub_f32_e32 v69, v69, v148
	v_add_f32_e32 v70, v61, v70
	v_exp_f32_e32 v69, v69
	v_add_f32_e32 v70, v66, v70
	v_add_f32_e32 v70, v67, v70
	v_add_f32_e32 v70, v68, v70
	v_add_f32_e32 v70, v69, v70
	v_cvt_pk_bf16_f32 v58, v58, v59
	v_cvt_pk_bf16_f32 v59, v60, v61
	v_cvt_pk_bf16_f32 v60, v66, v67
	v_cvt_pk_bf16_f32 v61, v68, v69
	v_bfe_u32 v104, v104, 3, 6
	v_or_b32_e32 v68, s6, v104
	v_mul_u32_u24_e32 v68, 0x8800, v68
	ds_bpermute_b32 v66, v106, v70
	v_lshlrev_b32_e32 v68, 1, v68
	v_mov_b32_e32 v69, v49
	v_lshl_add_u64 v[68:69], s[44:45], 0, v[68:69]
	v_lshl_add_u64 v[96:97], v[68:69], 0, v[48:49]
	v_lshl_add_u64 v[68:69], s[20:21], 1, v[96:97]
	s_lshl_b32 s2, s8, 1
	s_mov_b32 s3, s73
	v_lshl_add_u64 v[112:113], v[68:69], 0, s[2:3]
	s_waitcnt lgkmcnt(0)
	v_add_f32_e32 v66, v70, v66
	global_load_dwordx4 v[68:71], v[112:113], off
	global_load_dwordx4 v[72:75], v[112:113], off offset:128
	global_load_dwordx4 v[76:79], v[112:113], off offset:256
	global_load_dwordx4 v[80:83], v[112:113], off offset:384
	global_load_dwordx4 v[84:87], v[112:113], off offset:512
	global_load_dwordx4 v[88:91], v[112:113], off offset:640
	global_load_dwordx4 v[92:95], v[112:113], off offset:768
	global_load_dwordx4 v[108:111], v[112:113], off offset:896
	s_nop 0
	global_load_dwordx4 v[112:115], v[112:113], off offset:1024
	v_lshl_add_u64 v[96:97], s[10:11], 1, v[96:97]
	global_load_dwordx4 v[116:119], v[96:97], off
	global_load_dwordx4 v[120:123], v[96:97], off offset:128
	global_load_dwordx4 v[124:127], v[96:97], off offset:256
	global_load_dwordx4 v[128:131], v[96:97], off offset:384
	v_mul_u32_u24_e32 v48, 0xa0, v104
	ds_bpermute_b32 v67, v107, v66
	s_mov_b64 s[6:7], s[72:73]
	v_add_u32_e32 v48, v48, v102
	v_add_u32_e32 v48, 0x70, v48
	s_waitcnt vmcnt(12)
	ds_write_b128 v48, v[68:71]
	s_waitcnt vmcnt(11)
	ds_write_b128 v48, v[72:75] offset:10240
	s_waitcnt vmcnt(10)
	ds_write_b128 v48, v[76:79] offset:20480
	s_waitcnt vmcnt(9)
	ds_write_b128 v48, v[80:83] offset:30720
	s_waitcnt vmcnt(8)
	ds_write_b128 v48, v[84:87] offset:40960
	s_waitcnt vmcnt(7)
	ds_write_b128 v48, v[88:91] offset:51200
	s_waitcnt vmcnt(6)
	ds_write_b128 v48, v[92:95] offset:61440
	s_waitcnt vmcnt(5)
	v_add_u32_e32 v86, 0x11800, v48
	ds_write_b128 v86, v[108:111]
	s_waitcnt vmcnt(4)
	v_add_u32_e32 v86, 0x14000, v48
	ds_write_b128 v86, v[112:115]
	s_waitcnt vmcnt(3)
	v_add_u32_e32 v86, 0x16800, v48
	ds_write_b128 v86, v[116:119]
	s_waitcnt vmcnt(2)
	v_add_u32_e32 v86, 0x19000, v48
	ds_write_b128 v86, v[120:123]
	s_waitcnt vmcnt(1)
	v_add_u32_e32 v86, 0x1b800, v48
	ds_write_b128 v86, v[124:127]
	s_waitcnt vmcnt(0)
	v_add_u32_e32 v86, 0x1e000, v48
	ds_write_b128 v86, v[128:131]
	v_lshl_add_u32 v84, v105, 1, 0
	s_waitcnt lgkmcnt(0)
	s_barrier
; #define LAS __attribute__((address_space(3)))
; __device__ __forceinline__ f32x4 mfma16(bf16x8 a, bf16x8 b, f32x4 c) { return __builtin_amdgcn_mfma_f32_16x16x32_bf16(a, b, c, 0, 0, 0); }
; template <bool CTXQ>
; __device__ __forceinline__ void attn_super(const bf16_t* QO, bf16_t* OO, const bf16_t* Kb, const bf16_t* VT, const float* rpb, LAS unsigned char* lds, int tid_, int lane_, int wave, int st) {
;     ...
;     for (int grp = G0; grp < 16; ++grp) {
;         const int blk = grp < 8 ? krl0 + grp : 9 + ((grp - 8) >> 1), col = grp < 8 ? ks : 32 * ((grp - 8) & 1);
;         const bf16x8 pf = __builtin_bit_cast(bf16x8, P[grp]);
; #pragma unroll
;         for (int dt = 0; dt < 4; ++dt) {
;             const bf16x8 vf = *(const LAS bf16x8*)(lds + (blk * 64 + 16 * dt + q) * AT_PITCH + (col + 8 * g) * 2);
;             O[dt] = mfma16(vf, pf, O[dt]);
;         }
;         if (grp & 1) __builtin_amdgcn_sched_barrier(0);
;     }
	v_add_u32_e32 v48, 0x70, v84
	v_mul_u32_u24_e32 v87, 0xa0, v99
	v_add_u32_e32 v87, v87, v103
	v_add_u32_e32 v87, 0x70, v87
	v_or_b32_e32 v85, s29, v99
	v_mul_u32_u24_e32 v86, 0xa0, v85
	v_add_u32_e32 v86, v86, v48
	ds_read_b128 v[68:71], v86
	ds_read_b128 v[72:75], v86 offset:2560
	ds_read_b128 v[76:79], v86 offset:5120
	ds_read_b128 v[80:83], v86 offset:7680
	v_or_b32_e32 v85, s31, v99
	v_mul_u32_u24_e32 v86, 0xa0, v85
	v_add_u32_e32 v86, v86, v48
	ds_read_b128 v[88:91], v86
	ds_read_b128 v[92:95], v86 offset:2560
	ds_read_b128 v[108:111], v86 offset:5120
	ds_read_b128 v[112:115], v86 offset:7680
	s_waitcnt lgkmcnt(7)
	v_mfma_f32_16x16x32_bf16 v[116:119], v[68:71], v[4:7], 0
	v_or_b32_e32 v85, s35, v99
	v_mul_u32_u24_e32 v86, 0xa0, v85
	v_add_u32_e32 v86, v86, v48
	ds_read_b128 v[68:71], v86
	s_waitcnt lgkmcnt(7)
	v_mfma_f32_16x16x32_bf16 v[120:123], v[72:75], v[4:7], 0
	ds_read_b128 v[72:75], v86 offset:2560
	s_waitcnt lgkmcnt(7)
	v_mfma_f32_16x16x32_bf16 v[124:127], v[76:79], v[4:7], 0
	ds_read_b128 v[76:79], v86 offset:5120
	s_waitcnt lgkmcnt(7)
	v_mfma_f32_16x16x32_bf16 v[128:131], v[80:83], v[4:7], 0
	ds_read_b128 v[80:83], v86 offset:7680
	s_waitcnt lgkmcnt(7)
	v_mfma_f32_16x16x32_bf16 v[116:119], v[88:91], v[0:3], v[116:119]
	v_or_b32_e32 v85, s37, v99
	v_mul_u32_u24_e32 v86, 0xa0, v85
	v_add_u32_e32 v86, v86, v48
	ds_read_b128 v[88:91], v86
	s_waitcnt lgkmcnt(7)
	v_mfma_f32_16x16x32_bf16 v[120:123], v[92:95], v[0:3], v[120:123]
	ds_read_b128 v[92:95], v86 offset:2560
	s_waitcnt lgkmcnt(7)
	v_mfma_f32_16x16x32_bf16 v[124:127], v[108:111], v[0:3], v[124:127]
	ds_read_b128 v[108:111], v86 offset:5120
	s_waitcnt lgkmcnt(7)
	v_mfma_f32_16x16x32_bf16 v[128:131], v[112:115], v[0:3], v[128:131]
	ds_read_b128 v[112:115], v86 offset:7680
	s_waitcnt lgkmcnt(7)
	v_mfma_f32_16x16x32_bf16 v[116:119], v[68:71], v[8:11], v[116:119]
	v_or_b32_e32 v85, s39, v99
	v_mul_u32_u24_e32 v86, 0xa0, v85
	v_add_u32_e32 v86, v86, v48
	ds_read_b128 v[68:71], v86
	s_waitcnt lgkmcnt(7)
	v_mfma_f32_16x16x32_bf16 v[120:123], v[72:75], v[8:11], v[120:123]
	ds_read_b128 v[72:75], v86 offset:2560
	s_waitcnt lgkmcnt(7)
	v_mfma_f32_16x16x32_bf16 v[124:127], v[76:79], v[8:11], v[124:127]
	ds_read_b128 v[76:79], v86 offset:5120
	s_waitcnt lgkmcnt(7)
	v_mfma_f32_16x16x32_bf16 v[128:131], v[80:83], v[8:11], v[128:131]
	ds_read_b128 v[80:83], v86 offset:7680
	s_waitcnt lgkmcnt(7)
	v_mfma_f32_16x16x32_bf16 v[116:119], v[88:91], v[12:15], v[116:119]
	v_or_b32_e32 v85, s51, v99
	v_mul_u32_u24_e32 v86, 0xa0, v85
	v_add_u32_e32 v86, v86, v48
	ds_read_b128 v[88:91], v86
	s_waitcnt lgkmcnt(7)
	v_mfma_f32_16x16x32_bf16 v[120:123], v[92:95], v[12:15], v[120:123]
	ds_read_b128 v[92:95], v86 offset:2560
	s_waitcnt lgkmcnt(7)
	v_mfma_f32_16x16x32_bf16 v[124:127], v[108:111], v[12:15], v[124:127]
	ds_read_b128 v[108:111], v86 offset:5120
	s_waitcnt lgkmcnt(7)
	v_mfma_f32_16x16x32_bf16 v[128:131], v[112:115], v[12:15], v[128:131]
	ds_read_b128 v[112:115], v86 offset:7680
	s_waitcnt lgkmcnt(7)
	v_mfma_f32_16x16x32_bf16 v[116:119], v[68:71], v[16:19], v[116:119]
	v_or_b32_e32 v85, s55, v99
	v_mul_u32_u24_e32 v86, 0xa0, v85
	v_add_u32_e32 v86, v86, v48
	ds_read_b128 v[68:71], v86
	s_waitcnt lgkmcnt(7)
	v_mfma_f32_16x16x32_bf16 v[120:123], v[72:75], v[16:19], v[120:123]
	ds_read_b128 v[72:75], v86 offset:2560
	s_waitcnt lgkmcnt(7)
	v_mfma_f32_16x16x32_bf16 v[124:127], v[76:79], v[16:19], v[124:127]
	ds_read_b128 v[76:79], v86 offset:5120
	s_waitcnt lgkmcnt(7)
	v_mfma_f32_16x16x32_bf16 v[128:131], v[80:83], v[16:19], v[128:131]
	ds_read_b128 v[80:83], v86 offset:7680
	s_waitcnt lgkmcnt(7)
	v_mfma_f32_16x16x32_bf16 v[116:119], v[88:91], v[20:23], v[116:119]
	v_or_b32_e32 v85, s57, v99
	v_mul_u32_u24_e32 v86, 0xa0, v85
	v_add_u32_e32 v86, v86, v48
	ds_read_b128 v[88:91], v86
	s_waitcnt lgkmcnt(7)
	v_mfma_f32_16x16x32_bf16 v[120:123], v[92:95], v[20:23], v[120:123]
	ds_read_b128 v[92:95], v86 offset:2560
	s_waitcnt lgkmcnt(7)
	v_mfma_f32_16x16x32_bf16 v[124:127], v[108:111], v[20:23], v[124:127]
	ds_read_b128 v[108:111], v86 offset:5120
	s_waitcnt lgkmcnt(7)
	v_mfma_f32_16x16x32_bf16 v[128:131], v[112:115], v[20:23], v[128:131]
	ds_read_b128 v[112:115], v86 offset:7680
	s_waitcnt lgkmcnt(7)
	v_mfma_f32_16x16x32_bf16 v[116:119], v[68:71], v[24:27], v[116:119]
	v_add_u32_e32 v86, 0x16800, v87
	ds_read_b128 v[68:71], v86
	s_waitcnt lgkmcnt(7)
	v_mfma_f32_16x16x32_bf16 v[120:123], v[72:75], v[24:27], v[120:123]
	ds_read_b128 v[72:75], v86 offset:2560
	s_waitcnt lgkmcnt(7)
	v_mfma_f32_16x16x32_bf16 v[124:127], v[76:79], v[24:27], v[124:127]
	ds_read_b128 v[76:79], v86 offset:5120
	s_waitcnt lgkmcnt(7)
	v_mfma_f32_16x16x32_bf16 v[128:131], v[80:83], v[24:27], v[128:131]
	ds_read_b128 v[80:83], v86 offset:7680
	s_waitcnt lgkmcnt(7)
	v_mfma_f32_16x16x32_bf16 v[116:119], v[88:91], v[28:31], v[116:119]
	ds_read_b128 v[88:91], v86 offset:64
	s_waitcnt lgkmcnt(7)
	v_mfma_f32_16x16x32_bf16 v[120:123], v[92:95], v[28:31], v[120:123]
	ds_read_b128 v[92:95], v86 offset:2624
	s_waitcnt lgkmcnt(7)
	v_mfma_f32_16x16x32_bf16 v[124:127], v[108:111], v[28:31], v[124:127]
	ds_read_b128 v[108:111], v86 offset:5184
	s_waitcnt lgkmcnt(7)
; #define LAS __attribute__((address_space(3)))
; __device__ __forceinline__ unsigned pk2(float lo, float hi) { unsigned r; asm("v_cvt_pk_bf16_f32 %0, %1, %2" : "=v"(r) : "v"(lo), "v"(hi)); return r; }
; __device__ __forceinline__ f32x4 mfma16(bf16x8 a, bf16x8 b, f32x4 c) { return __builtin_amdgcn_mfma_f32_16x16x32_bf16(a, b, c, 0, 0, 0); }
; template <bool CTXQ>
; __device__ __forceinline__ void attn_super(const bf16_t* QO, bf16_t* OO, const bf16_t* Kb, const bf16_t* VT, const float* rpb, LAS unsigned char* lds, int tid_, int lane_, int wave, int st) {
;     ...
;     for (int grp = G0; grp < 16; ++grp) {
;         const int blk = grp < 8 ? krl0 + grp : 9 + ((grp - 8) >> 1), col = grp < 8 ? ks : 32 * ((grp - 8) & 1);
;         const bf16x8 pf = __builtin_bit_cast(bf16x8, P[grp]);
; #pragma unroll
;         for (int dt = 0; dt < 4; ++dt) {
;             const bf16x8 vf = *(const LAS bf16x8*)(lds + (blk * 64 + 16 * dt + q) * AT_PITCH + (col + 8 * g) * 2);
;             O[dt] = mfma16(vf, pf, O[dt]);
;         }
;         if (grp & 1) __builtin_amdgcn_sched_barrier(0);
;     }
;     const float inv = __builtin_amdgcn_rcpf(sum);
; #pragma unroll
;     for (int dt = 0; dt < 4; ++dt) { u32x2 w; w.x = pk2(O[dt][0] * inv, O[dt][1] * inv); w.y = pk2(O[dt][2] * inv, O[dt][3] * inv);
;         *(u32x2*)(OO + qrow * DM + h * 64 + 16 * dt + 4 * g) = w; }
;     __syncthreads();
	v_mfma_f32_16x16x32_bf16 v[128:131], v[112:115], v[28:31], v[128:131]
	ds_read_b128 v[112:115], v86 offset:7744
	s_waitcnt lgkmcnt(7)
	v_mfma_f32_16x16x32_bf16 v[116:119], v[68:71], v[32:35], v[116:119]
	v_add_u32_e32 v86, 0x19000, v87
	ds_read_b128 v[68:71], v86
	s_waitcnt lgkmcnt(7)
	v_mfma_f32_16x16x32_bf16 v[120:123], v[72:75], v[32:35], v[120:123]
	ds_read_b128 v[72:75], v86 offset:2560
	s_waitcnt lgkmcnt(7)
	v_mfma_f32_16x16x32_bf16 v[124:127], v[76:79], v[32:35], v[124:127]
	ds_read_b128 v[76:79], v86 offset:5120
	s_waitcnt lgkmcnt(7)
	v_mfma_f32_16x16x32_bf16 v[128:131], v[80:83], v[32:35], v[128:131]
	ds_read_b128 v[80:83], v86 offset:7680
	s_waitcnt lgkmcnt(7)
	v_mfma_f32_16x16x32_bf16 v[116:119], v[88:91], v[36:39], v[116:119]
	ds_read_b128 v[88:91], v86 offset:64
	s_waitcnt lgkmcnt(7)
	v_mfma_f32_16x16x32_bf16 v[120:123], v[92:95], v[36:39], v[120:123]
	ds_read_b128 v[92:95], v86 offset:2624
	s_waitcnt lgkmcnt(7)
	v_mfma_f32_16x16x32_bf16 v[124:127], v[108:111], v[36:39], v[124:127]
	ds_read_b128 v[108:111], v86 offset:5184
	s_waitcnt lgkmcnt(7)
	v_mfma_f32_16x16x32_bf16 v[128:131], v[112:115], v[36:39], v[128:131]
	ds_read_b128 v[112:115], v86 offset:7744
	s_waitcnt lgkmcnt(7)
	v_mfma_f32_16x16x32_bf16 v[116:119], v[68:71], v[40:43], v[116:119]
	v_add_u32_e32 v86, 0x1b800, v87
	ds_read_b128 v[68:71], v86
	s_waitcnt lgkmcnt(7)
	v_mfma_f32_16x16x32_bf16 v[120:123], v[72:75], v[40:43], v[120:123]
	ds_read_b128 v[72:75], v86 offset:2560
	s_waitcnt lgkmcnt(7)
	v_mfma_f32_16x16x32_bf16 v[124:127], v[76:79], v[40:43], v[124:127]
	ds_read_b128 v[76:79], v86 offset:5120
	s_waitcnt lgkmcnt(7)
	v_mfma_f32_16x16x32_bf16 v[128:131], v[80:83], v[40:43], v[128:131]
	ds_read_b128 v[80:83], v86 offset:7680
	s_waitcnt lgkmcnt(7)
	v_mfma_f32_16x16x32_bf16 v[116:119], v[88:91], v[44:47], v[116:119]
	ds_read_b128 v[88:91], v86 offset:64
	s_waitcnt lgkmcnt(7)
	v_mfma_f32_16x16x32_bf16 v[120:123], v[92:95], v[44:47], v[120:123]
	ds_read_b128 v[92:95], v86 offset:2624
	s_waitcnt lgkmcnt(7)
	v_mfma_f32_16x16x32_bf16 v[124:127], v[108:111], v[44:47], v[124:127]
	ds_read_b128 v[108:111], v86 offset:5184
	s_waitcnt lgkmcnt(7)
	v_mfma_f32_16x16x32_bf16 v[128:131], v[112:115], v[44:47], v[128:131]
	ds_read_b128 v[112:115], v86 offset:7744
	s_waitcnt lgkmcnt(7)
	v_mfma_f32_16x16x32_bf16 v[116:119], v[68:71], v[50:53], v[116:119]
	v_add_u32_e32 v86, 0x1e000, v87
	ds_read_b128 v[68:71], v86
	s_waitcnt lgkmcnt(7)
	v_mfma_f32_16x16x32_bf16 v[120:123], v[72:75], v[50:53], v[120:123]
	ds_read_b128 v[72:75], v86 offset:2560
	s_waitcnt lgkmcnt(7)
	v_mfma_f32_16x16x32_bf16 v[124:127], v[76:79], v[50:53], v[124:127]
	ds_read_b128 v[76:79], v86 offset:5120
	s_waitcnt lgkmcnt(7)
	v_mfma_f32_16x16x32_bf16 v[128:131], v[80:83], v[50:53], v[128:131]
	ds_read_b128 v[80:83], v86 offset:7680
	s_waitcnt lgkmcnt(7)
	v_mfma_f32_16x16x32_bf16 v[116:119], v[88:91], v[54:57], v[116:119]
	ds_read_b128 v[88:91], v86 offset:64
	s_waitcnt lgkmcnt(7)
	v_mfma_f32_16x16x32_bf16 v[120:123], v[92:95], v[54:57], v[120:123]
	ds_read_b128 v[92:95], v86 offset:2624
	s_waitcnt lgkmcnt(7)
	v_mfma_f32_16x16x32_bf16 v[124:127], v[108:111], v[54:57], v[124:127]
	ds_read_b128 v[108:111], v86 offset:5184
	s_waitcnt lgkmcnt(7)
	v_mfma_f32_16x16x32_bf16 v[128:131], v[112:115], v[54:57], v[128:131]
	ds_read_b128 v[112:115], v86 offset:7744
	s_waitcnt lgkmcnt(7)
	v_mfma_f32_16x16x32_bf16 v[116:119], v[68:71], v[62:65], v[116:119]
	s_waitcnt lgkmcnt(6)
	v_mfma_f32_16x16x32_bf16 v[120:123], v[72:75], v[62:65], v[120:123]
	s_waitcnt lgkmcnt(5)
	v_mfma_f32_16x16x32_bf16 v[124:127], v[76:79], v[62:65], v[124:127]
	s_waitcnt lgkmcnt(4)
	v_mfma_f32_16x16x32_bf16 v[128:131], v[80:83], v[62:65], v[128:131]
	s_waitcnt lgkmcnt(3)
	v_mfma_f32_16x16x32_bf16 v[4:7], v[88:91], v[58:61], v[116:119]
	s_waitcnt lgkmcnt(2)
	v_mfma_f32_16x16x32_bf16 v[8:11], v[92:95], v[58:61], v[120:123]
	s_waitcnt lgkmcnt(1)
	v_mfma_f32_16x16x32_bf16 v[12:15], v[108:111], v[58:61], v[124:127]
	s_waitcnt lgkmcnt(0)
	v_mfma_f32_16x16x32_bf16 v[0:3], v[112:115], v[58:61], v[128:131]
	v_add_f32_e32 v16, v66, v67
	v_rcp_f32_e32 v18, v16
	v_lshl_add_u64 v[16:17], v[100:101], 1, s[42:43]
	v_lshl_add_u64 v[16:17], v[16:17], 0, s[6:7]
	v_mov_b32_e32 v99, v49
	v_mul_f32_e32 v4, v18, v4
	v_mul_f32_e32 v5, v18, v5
	v_cvt_pk_bf16_f32 v4, v4, v5
	v_mul_f32_e32 v5, v18, v6
	v_lshl_add_u64 v[16:17], v[16:17], 0, v[98:99]
	v_mul_f32_e32 v6, v18, v7
	v_cvt_pk_bf16_f32 v5, v5, v6
	global_store_dwordx2 v[16:17], v[4:5], off
	v_mul_f32_e32 v4, v18, v8
	v_mul_f32_e32 v5, v18, v9
	v_cvt_pk_bf16_f32 v4, v4, v5
	v_mul_f32_e32 v5, v18, v10
	v_mul_f32_e32 v6, v18, v11
	v_cvt_pk_bf16_f32 v5, v5, v6
	global_store_dwordx2 v[16:17], v[4:5], off offset:32
	v_mul_f32_e32 v4, v18, v12
	v_mul_f32_e32 v5, v18, v13
	v_mul_f32_e32 v0, v18, v0
	v_mul_f32_e32 v1, v18, v1
	s_addk_i32 s64, 0x100
	v_cvt_pk_bf16_f32 v4, v4, v5
	v_mul_f32_e32 v5, v18, v14
	v_cvt_pk_bf16_f32 v0, v0, v1
	v_mul_f32_e32 v1, v18, v2
	s_cmpk_eq_i32 s64, 0x1000
	v_mul_f32_e32 v6, v18, v15
	v_cvt_pk_bf16_f32 v5, v5, v6
	global_store_dwordx2 v[16:17], v[4:5], off offset:64
	v_mul_f32_e32 v2, v18, v3
	v_cvt_pk_bf16_f32 v1, v1, v2
	global_store_dwordx2 v[16:17], v[0:1], off offset:96
	s_barrier
	s_cbranch_scc1 .LBB0_221
